# P5: fragment ring loads stay in flight across q staging and step A (on top of sc1 stores + chunk GEMM prologue trims)
# baseline (speedup 1.0000x reference)
.Lp5_kpersist:
	v_and_b32_e32 v99, 31, v170
	v_and_b32_e32 v171, 63, v170
	v_or_b32_e32 v3, s47, v99
	s_lshl_b32 s26, s75, 6
	s_lshl_b32 s6, s75, 2
	v_lshrrev_b32_e32 v2, 5, v171
	v_lshl_add_u32 v95, v3, 8, 0
	s_add_i32 s6, s6, 4
	v_or_b32_e32 v90, s26, v3
	v_mad_u32_u24 v91, v3, s68, v95
	v_xor_b32_e32 v3, v2, v169
	v_bitop3_b32 v4, v2, v169, 2 bitop3:0x36
	v_bitop3_b32 v5, v2, v169, 4 bitop3:0x36
	v_bitop3_b32 v6, v2, v169, 6 bitop3:0x36
	v_bitop3_b32 v7, v2, v169, 8 bitop3:0x36
	v_bitop3_b32 v8, v2, v169, 10 bitop3:0x36
	v_bitop3_b32 v9, v2, v169, 12 bitop3:0x36
	v_bitop3_b32 v10, v2, v169, 14 bitop3:0x36
	v_lshlrev_b32_e32 v94, 2, v2
	s_cmp_ge_u32 s54, s6
	v_lshlrev_b32_e32 v92, 3, v2
	v_lshlrev_b32_e32 v103, 4, v3
	v_lshlrev_b32_e32 v102, 4, v4
	v_lshlrev_b32_e32 v101, 4, v5
	v_lshlrev_b32_e32 v100, 4, v6
	v_lshlrev_b32_e32 v98, 4, v7
	v_lshlrev_b32_e32 v97, 4, v8
	v_lshlrev_b32_e32 v96, 4, v9
	v_lshlrev_b32_e32 v93, 4, v10
	s_waitcnt lgkmcnt(0)
	s_barrier
	s_cbranch_scc1 .LBB0_454
	v_or_b32_e32 v2, s49, v99
	s_add_i32 s7, 0, 0x10800
	v_lshl_add_u32 v116, v2, 8, s7
	v_add_u32_e32 v2, v116, v103
	ds_read_b128 v[2:5], v2
	v_add_u32_e32 v6, v95, v103
	ds_read_b128 v[6:9], v6
	v_add_u32_e32 v104, v116, v102
	ds_read_b128 v[104:107], v104
	v_add_u32_e32 v108, v95, v102
	ds_read_b128 v[108:111], v108
	v_add_u32_e32 v112, v116, v101
	s_waitcnt lgkmcnt(2)
	v_mfma_f32_32x32x16_bf16 v[2:17], v[2:5], v[6:9], 0
	v_add_u32_e32 v117, v95, v96
	v_add_u32_e32 v118, v95, v93
	v_or_b32_e32 v119, s49, v94
	v_cmp_le_u32_e32 vcc, v119, v90
	v_or_b32_e32 v121, 2, v119
	v_or_b32_e32 v122, 8, v119
	v_add3_u32 v120, v91, v92, s50
	s_waitcnt lgkmcnt(0)
	v_mfma_f32_32x32x16_bf16 v[2:17], v[104:107], v[108:111], v[2:17]
	ds_read_b128 v[104:107], v112
	v_add_u32_e32 v108, v95, v101
	ds_read_b128 v[108:111], v108
	v_add_u32_e32 v112, v116, v100
	s_waitcnt lgkmcnt(0)
	v_mfma_f32_32x32x16_bf16 v[2:17], v[104:107], v[108:111], v[2:17]
	ds_read_b128 v[104:107], v112
	v_add_u32_e32 v108, v95, v100
	ds_read_b128 v[108:111], v108
	v_add_u32_e32 v112, v116, v98
	s_waitcnt lgkmcnt(0)
	v_mfma_f32_32x32x16_bf16 v[2:17], v[104:107], v[108:111], v[2:17]
	ds_read_b128 v[104:107], v112
	v_add_u32_e32 v108, v95, v98
	ds_read_b128 v[108:111], v108
	v_add_u32_e32 v112, v116, v97
	ds_read_b128 v[112:115], v112
	s_waitcnt lgkmcnt(1)
	v_mfma_f32_32x32x16_bf16 v[2:17], v[104:107], v[108:111], v[2:17]
	v_add_u32_e32 v104, v95, v97
	ds_read_b128 v[104:107], v104
	v_add_u32_e32 v108, v116, v96
	ds_read_b128 v[108:111], v108
	s_waitcnt lgkmcnt(1)
	v_mfma_f32_32x32x16_bf16 v[2:17], v[112:115], v[104:107], v[2:17]
	ds_read_b128 v[104:107], v117
	v_add_u32_e32 v112, v116, v93
	ds_read_b128 v[112:115], v112
	v_or_b32_e32 v117, 3, v119
	v_or_b32_e32 v116, 16, v119
	s_waitcnt lgkmcnt(1)
	v_mfma_f32_32x32x16_bf16 v[2:17], v[108:111], v[104:107], v[2:17]
	ds_read_b128 v[104:107], v118
	v_or_b32_e32 v108, 9, v119
	v_or_b32_e32 v109, 10, v119
	v_or_b32_e32 v110, 11, v119
	v_add_u32_e32 v111, 0x4000, v120
	v_or_b32_e32 v118, 17, v119
	s_waitcnt lgkmcnt(0)
	v_mfma_f32_32x32x16_bf16 v[2:17], v[112:115], v[104:107], v[2:17]
	s_nop 11
	v_cndmask_b32_e32 v2, 0, v2, vcc
	v_cmp_lt_u32_e32 vcc, v119, v90
	s_nop 1
	v_cndmask_b32_e32 v3, 0, v3, vcc
	v_cmp_le_u32_e32 vcc, v121, v90
	v_cvt_pk_bf16_f32 v2, v2, v3
	s_nop 0
	v_cndmask_b32_e32 v4, 0, v4, vcc
	v_cmp_le_u32_e32 vcc, v117, v90
	s_nop 1
	v_cndmask_b32_e32 v5, 0, v5, vcc
	v_cmp_le_u32_e32 vcc, v122, v90
	v_cvt_pk_bf16_f32 v3, v4, v5
	s_nop 0
	v_cndmask_b32_e32 v6, 0, v6, vcc
	v_cmp_le_u32_e32 vcc, v108, v90
	s_nop 1
	v_cndmask_b32_e32 v7, 0, v7, vcc
	v_cmp_le_u32_e32 vcc, v109, v90
	v_cvt_pk_bf16_f32 v4, v6, v7
	v_or_b32_e32 v6, 26, v119
	v_cndmask_b32_e32 v8, 0, v8, vcc
	v_cmp_le_u32_e32 vcc, v110, v90
	v_or_b32_e32 v7, 27, v119
	s_nop 0
	v_cndmask_b32_e32 v9, 0, v9, vcc
	v_cmp_le_u32_e32 vcc, v116, v90
	v_cvt_pk_bf16_f32 v5, v8, v9
	ds_write2_b64 v111, v[2:3], v[4:5] offset1:2
	v_cndmask_b32_e32 v10, 0, v10, vcc
	v_cmp_le_u32_e32 vcc, v118, v90
	v_or_b32_e32 v2, 18, v119
	v_or_b32_e32 v5, 25, v119
	v_cndmask_b32_e32 v11, 0, v11, vcc
	v_cmp_le_u32_e32 vcc, v2, v90
	v_or_b32_e32 v2, 19, v119
	s_nop 0
	v_cndmask_b32_e32 v3, 0, v12, vcc
	v_cmp_le_u32_e32 vcc, v2, v90
	v_cvt_pk_bf16_f32 v2, v10, v11
	s_nop 0
	v_cndmask_b32_e32 v4, 0, v13, vcc
	v_cvt_pk_bf16_f32 v3, v3, v4
	v_or_b32_e32 v4, 24, v119
	v_cmp_le_u32_e32 vcc, v4, v90
	s_nop 1
	v_cndmask_b32_e32 v4, 0, v14, vcc
	v_cmp_le_u32_e32 vcc, v5, v90
	s_nop 1
	v_cndmask_b32_e32 v5, 0, v15, vcc
	v_cmp_le_u32_e32 vcc, v6, v90
	v_cvt_pk_bf16_f32 v4, v4, v5
	s_nop 0
	v_cndmask_b32_e32 v6, 0, v16, vcc
	v_cmp_le_u32_e32 vcc, v7, v90
	s_nop 1
	v_cndmask_b32_e32 v7, 0, v17, vcc
	v_cvt_pk_bf16_f32 v5, v6, v7
	ds_write2_b64 v111, v[2:3], v[4:5] offset0:4 offset1:6

.LBB0_456:
	v_bfe_u32 v138, v170, 4, 2
	v_lshl_add_u32 v139, v169, 8, 0
	v_xor_b32_e32 v2, v138, v169
	s_lshl_b32 s6, s74, 3
	v_lshl_add_u32 v98, v2, 4, v139
	s_ashr_i32 s7, s6, 31
	s_waitcnt lgkmcnt(0)
	s_barrier
	ds_read_b128 v[2:5], v98
	ds_read_b128 v[10:13], v98 offset:4096
	ds_read_b128 v[90:93], v98 offset:8192
	ds_read_b128 v[98:101], v98 offset:12288
	s_lshl_b64 s[6:7], s[6:7], 11
	s_lshl_b32 s73, s73, 9
	s_add_u32 s8, s73, s31
	s_addc_u32 s9, 0, s46
	s_add_u32 s6, s8, s6
	s_addc_u32 s7, s9, s7
	s_waitcnt lgkmcnt(3)
	s_waitcnt vmcnt(0)
	v_mfma_f32_16x16x32_bf16 v[6:9], v[66:69], v[2:5], 0
	v_mov_b32_e32 v123, s7
	v_or_b32_e32 v122, s6, v169
	v_lshlrev_b32_e32 v124, 3, v138
	s_waitcnt lgkmcnt(2)
	v_mfma_f32_16x16x32_bf16 v[14:17], v[66:69], v[10:13], 0
	v_lshlrev_b64 v[122:123], 6, v[122:123]
	v_lshl_add_u64 v[122:123], s[20:21], 0, v[122:123]
	v_lshlrev_b32_e32 v124, 1, v124
	s_waitcnt lgkmcnt(1)
	v_mfma_f32_16x16x32_bf16 v[94:97], v[66:69], v[90:93], 0
	v_mov_b32_e32 v125, v163
	v_lshl_add_u64 v[166:167], v[122:123], 0, v[124:125]
	s_waitcnt lgkmcnt(0)
	v_mfma_f32_16x16x32_bf16 v[66:69], v[66:69], v[98:101], 0
	v_mfma_f32_16x16x32_bf16 v[102:105], v[86:89], v[2:5], 0
	v_mfma_f32_16x16x32_bf16 v[106:109], v[86:89], v[10:13], 0
	v_mfma_f32_16x16x32_bf16 v[110:113], v[86:89], v[90:93], 0
	v_mfma_f32_16x16x32_bf16 v[86:89], v[86:89], v[98:101], 0
	v_mfma_f32_16x16x32_bf16 v[114:117], v[46:49], v[2:5], 0
	v_mfma_f32_16x16x32_bf16 v[118:121], v[46:49], v[10:13], 0
	v_mfma_f32_16x16x32_bf16 v[140:143], v[46:49], v[90:93], 0
	v_mfma_f32_16x16x32_bf16 v[46:49], v[46:49], v[98:101], 0
	v_mfma_f32_16x16x32_bf16 v[2:5], v[42:45], v[2:5], 0
	v_mfma_f32_16x16x32_bf16 v[10:13], v[42:45], v[10:13], 0
	v_mfma_f32_16x16x32_bf16 v[90:93], v[42:45], v[90:93], 0
	v_mfma_f32_16x16x32_bf16 v[42:45], v[42:45], v[98:101], 0
	global_load_dwordx4 v[134:137], v[166:167], off
	global_load_dwordx4 v[130:133], v[166:167], off offset:1024
	global_load_dwordx4 v[126:129], v[166:167], off offset:2048
	global_load_dwordx4 v[122:125], v[166:167], off offset:3072
	v_bitop3_b32 v98, v138, v169, 4 bitop3:0x36
	v_lshl_add_u32 v152, v98, 4, v139
	ds_read_b128 v[98:101], v152
	ds_read_b128 v[144:147], v152 offset:4096
	ds_read_b128 v[148:151], v152 offset:8192
	ds_read_b128 v[152:155], v152 offset:12288
	s_waitcnt lgkmcnt(3)
	v_mfma_f32_16x16x32_bf16 v[6:9], v[34:37], v[98:101], v[6:9]
	s_waitcnt lgkmcnt(2)
	v_mfma_f32_16x16x32_bf16 v[14:17], v[34:37], v[144:147], v[14:17]
	s_waitcnt lgkmcnt(1)
	v_mfma_f32_16x16x32_bf16 v[94:97], v[34:37], v[148:151], v[94:97]
	s_waitcnt lgkmcnt(0)
	v_mfma_f32_16x16x32_bf16 v[34:37], v[34:37], v[152:155], v[66:69]
	v_mfma_f32_16x16x32_bf16 v[66:69], v[38:41], v[98:101], v[102:105]
	v_mfma_f32_16x16x32_bf16 v[102:105], v[38:41], v[144:147], v[106:109]
	v_mfma_f32_16x16x32_bf16 v[156:159], v[38:41], v[148:151], v[110:113]
	v_mfma_f32_16x16x32_bf16 v[38:41], v[38:41], v[152:155], v[86:89]
	v_mfma_f32_16x16x32_bf16 v[86:89], v[26:29], v[98:101], v[114:117]
	v_mfma_f32_16x16x32_bf16 v[98:101], v[30:33], v[98:101], v[2:5]
	v_mfma_f32_16x16x32_bf16 v[172:175], v[26:29], v[144:147], v[118:121]
	v_mfma_f32_16x16x32_bf16 v[140:143], v[26:29], v[148:151], v[140:143]
	v_mfma_f32_16x16x32_bf16 v[176:179], v[26:29], v[152:155], v[46:49]
	v_mfma_f32_16x16x32_bf16 v[144:147], v[30:33], v[144:147], v[10:13]
	v_mfma_f32_16x16x32_bf16 v[148:151], v[30:33], v[148:151], v[90:93]
	v_mfma_f32_16x16x32_bf16 v[152:155], v[30:33], v[152:155], v[42:45]
	v_add_co_u32_e32 v2, vcc, s69, v166
	s_nop 1
	v_addc_co_u32_e32 v3, vcc, 0, v167, vcc
	global_load_dwordx4 v[118:121], v[2:3], off
	global_load_dwordx4 v[114:117], v[2:3], off offset:1024
	global_load_dwordx4 v[110:113], v[2:3], off offset:2048
	global_load_dwordx4 v[106:109], v[2:3], off offset:3072
	v_bitop3_b32 v2, v138, v169, 8 bitop3:0x36
	v_lshl_add_u32 v26, v2, 4, v139
	ds_read_b128 v[90:93], v26
	ds_read_b128 v[180:183], v26 offset:4096
	ds_read_b128 v[184:187], v26 offset:8192
	ds_read_b128 v[188:191], v26 offset:12288
	s_waitcnt lgkmcnt(3)
	v_mfma_f32_16x16x32_bf16 v[2:5], v[82:85], v[90:93], v[6:9]
	s_waitcnt lgkmcnt(2)
	v_mfma_f32_16x16x32_bf16 v[6:9], v[82:85], v[180:183], v[14:17]
	s_waitcnt lgkmcnt(1)
	v_mfma_f32_16x16x32_bf16 v[10:13], v[82:85], v[184:187], v[94:97]
	s_waitcnt lgkmcnt(0)
	v_mfma_f32_16x16x32_bf16 v[14:17], v[82:85], v[188:191], v[34:37]
	v_mfma_f32_16x16x32_bf16 v[26:29], v[74:77], v[90:93], v[66:69]
	v_mfma_f32_16x16x32_bf16 v[30:33], v[74:77], v[180:183], v[102:105]
	v_mfma_f32_16x16x32_bf16 v[34:37], v[74:77], v[184:187], v[156:159]
	v_mfma_f32_16x16x32_bf16 v[38:41], v[74:77], v[188:191], v[38:41]
	v_mfma_f32_16x16x32_bf16 v[42:45], v[78:81], v[90:93], v[86:89]
	v_mfma_f32_16x16x32_bf16 v[46:49], v[78:81], v[180:183], v[172:175]
	v_mfma_f32_16x16x32_bf16 v[66:69], v[78:81], v[184:187], v[140:143]
	v_mfma_f32_16x16x32_bf16 v[86:89], v[78:81], v[188:191], v[176:179]
	v_mfma_f32_16x16x32_bf16 v[90:93], v[70:73], v[90:93], v[98:101]
	v_mfma_f32_16x16x32_bf16 v[94:97], v[70:73], v[180:183], v[144:147]
	v_mfma_f32_16x16x32_bf16 v[98:101], v[70:73], v[184:187], v[148:151]
	v_mfma_f32_16x16x32_bf16 v[102:105], v[70:73], v[188:191], v[152:155]
	s_cmp_lg_u32 s75, 0
	s_cselect_b64 s[6:7], -1, 0
	s_cmp_eq_u32 s75, 0
	s_cbranch_scc1 .LBB0_458
	v_add_co_u32_e32 v70, vcc, 0x40000, v166
	s_nop 1
	v_addc_co_u32_e32 v71, vcc, 0, v167, vcc
	global_load_dwordx4 v[82:85], v[70:71], off
	global_load_dwordx4 v[74:77], v[70:71], off offset:1024
	global_load_dwordx4 v[78:81], v[70:71], off offset:2048
	s_nop 0
	global_load_dwordx4 v[70:73], v[70:71], off offset:3072
